# grid-barrier poll tightening: s_sleep removed from the 25 barrier poll loops (on top of the epilogue priority scheme)
# baseline (speedup 1.0000x reference)
.LBB0_14:
	global_load_dword v2, v0, s[6:7] offset:32 sc1
	s_waitcnt vmcnt(0)
	v_and_b32_e32 v2, 0xffff0000, v2
	v_cmp_ne_u32_e32 vcc, v2, v1
	s_or_b64 s[12:13], vcc, s[12:13]
	s_andn2_b64 exec, exec, s[12:13]
	s_cbranch_execnz .LBB0_14

; __device__ __forceinline__ unsigned xb_ld(unsigned* p)              { return __hip_atomic_load(p, __ATOMIC_RELAXED, __HIP_MEMORY_SCOPE_AGENT); }
; __device__ __forceinline__ void xcd_barrier_complete(unsigned* bar, unsigned x, unsigned& nloc, unsigned& nx) {
;     const unsigned G = gridDim.x * gridDim.y * gridDim.z;
;     unsigned sum, cnt, mine, sp = 0u;
;     for (;;) {
;         sum = 0u; cnt = 0u; mine = 0u;
; #pragma unroll
;         for (unsigned j = 0; j < 16; ++j) { const unsigned c = xb_ld(&bar[XB_XCNT(j)]); sum += c; cnt += (c > 0u) ? 1u : 0u; mine = (j == x) ? c : mine; }
;         if (sum == G) break;
;         __builtin_amdgcn_s_sleep(1);
;         if ((++sp & 255u) == 0u) { if (xb_ld(&bar[XB_TMO])) break; if (sp > XB_SPIN_CAP) { atomicAdd(&bar[XB_TMO], 1u); break; } }
;     }
;     nloc = mine > 0u ? mine : 1u; nx = cnt > 0u ? cnt : 1u;
; }
.LBB0_58:
	global_load_dword v15, v16, s[10:11] offset:1024 sc1
	s_waitcnt lgkmcnt(0)
	global_load_dword v0, v16, s[10:11] offset:1280 sc1
	global_load_dword v1, v16, s[10:11] offset:1536 sc1
	global_load_dword v2, v16, s[10:11] offset:1792 sc1
	global_load_dword v3, v16, s[10:11] offset:2048 sc1
	global_load_dword v4, v16, s[10:11] offset:2304 sc1
	global_load_dword v5, v16, s[10:11] offset:2560 sc1
	global_load_dword v6, v16, s[10:11] offset:2816 sc1
	global_load_dword v7, v16, s[10:11] offset:3072 sc1
	global_load_dword v8, v16, s[10:11] offset:3328 sc1
	global_load_dword v9, v16, s[10:11] offset:3584 sc1
	global_load_dword v10, v16, s[10:11] offset:3840 sc1
	global_load_dword v11, v16, s[4:5] sc1
	global_load_dword v12, v16, s[6:7] sc1
	global_load_dword v13, v16, s[12:13] sc1
	global_load_dword v14, v16, s[14:15] sc1
	s_mov_b64 s[16:17], -1
	s_mov_b64 s[18:19], -1
	s_waitcnt vmcnt(14)
	v_add_u32_e32 v17, v0, v15
	s_waitcnt vmcnt(13)
	v_add_u32_e32 v17, v17, v1
	s_waitcnt vmcnt(12)
	v_add_u32_e32 v17, v17, v2
	s_waitcnt vmcnt(11)
	v_add_u32_e32 v17, v17, v3
	s_waitcnt vmcnt(10)
	v_add_u32_e32 v17, v17, v4
	s_waitcnt vmcnt(9)
	v_add_u32_e32 v17, v17, v5
	s_waitcnt vmcnt(8)
	v_add_u32_e32 v17, v17, v6
	s_waitcnt vmcnt(7)
	v_add_u32_e32 v17, v17, v7
	s_waitcnt vmcnt(6)
	v_add_u32_e32 v17, v17, v8
	s_waitcnt vmcnt(5)
	v_add_u32_e32 v17, v17, v9
	s_waitcnt vmcnt(4)
	v_add_u32_e32 v17, v17, v10
	s_waitcnt vmcnt(3)
	v_add_u32_e32 v17, v17, v11
	s_waitcnt vmcnt(2)
	v_add_u32_e32 v17, v17, v12
	s_waitcnt vmcnt(1)
	v_add_u32_e32 v17, v17, v13
	s_waitcnt vmcnt(0)
	v_add_u32_e32 v17, v17, v14
	v_cmp_eq_u32_e32 vcc, s22, v17
	s_cbranch_vccnz .LBB0_57
	s_and_b32 s16, s23, 0xff
	s_cmp_eq_u32 s16, 0
	s_mov_b64 s[16:17], -1
	s_mov_b64 s[20:21], -1
	s_cbranch_scc0 .LBB0_62
	global_load_dword v17, v16, s[10:11] offset:512 sc1
	s_waitcnt vmcnt(0)
	v_cmp_eq_u32_e32 vcc, 0, v17
	s_cbranch_vccnz .LBB0_64
	s_mov_b64 s[20:21], 0

.LBB0_76:
	s_and_b32 s24, s28, 0xff
	s_mov_b64 s[22:23], -1
	s_cmp_lg_u32 s24, 0
	s_mov_b64 s[26:27], -1
	s_cbranch_scc1 .LBB0_79
	global_load_dword v2, v0, s[10:11] offset:512 sc1
	s_waitcnt vmcnt(0)
	v_cmp_eq_u32_e32 vcc, 0, v2
	s_cbranch_vccnz .LBB0_81
	s_mov_b64 s[26:27], 0
	s_mov_b64 s[24:25], -1

.LBB0_93:
	s_and_b32 s26, s34, 0xff
	s_cmp_lg_u32 s26, 0
	s_mov_b64 s[28:29], -1
	s_cbranch_scc1 .LBB0_96
	global_load_dword v1, v0, s[18:19] sc1
	s_waitcnt vmcnt(0)
	v_cmp_eq_u32_e32 vcc, 0, v1
	s_cbranch_vccnz .LBB0_98
	s_mov_b64 s[28:29], 0
	s_mov_b64 s[26:27], -1

; __device__ __forceinline__ unsigned xb_ld(unsigned* p)              { return __hip_atomic_load(p, __ATOMIC_RELAXED, __HIP_MEMORY_SCOPE_AGENT); }
; __device__ __forceinline__ void xcd_barrier_complete(unsigned* bar, unsigned x, unsigned& nloc, unsigned& nx) {
;     const unsigned G = gridDim.x * gridDim.y * gridDim.z;
;     unsigned sum, cnt, mine, sp = 0u;
;     for (;;) {
;         sum = 0u; cnt = 0u; mine = 0u;
; #pragma unroll
;         for (unsigned j = 0; j < 16; ++j) { const unsigned c = xb_ld(&bar[XB_XCNT(j)]); sum += c; cnt += (c > 0u) ? 1u : 0u; mine = (j == x) ? c : mine; }
;         if (sum == G) break;
;         __builtin_amdgcn_s_sleep(1);
;         if ((++sp & 255u) == 0u) { if (xb_ld(&bar[XB_TMO])) break; if (sp > XB_SPIN_CAP) { atomicAdd(&bar[XB_TMO], 1u); break; } }
;     }
;     nloc = mine > 0u ? mine : 1u; nx = cnt > 0u ? cnt : 1u;
; }
.LBB0_391:
	global_load_dword v16, v1, s[10:11] offset:1024 sc1
	global_load_dword v0, v1, s[10:11] offset:1280 sc1
	s_waitcnt lgkmcnt(0)
	global_load_dword v2, v1, s[10:11] offset:1536 sc1
	global_load_dword v3, v1, s[10:11] offset:1792 sc1
	global_load_dword v4, v1, s[10:11] offset:2048 sc1
	global_load_dword v5, v1, s[10:11] offset:2304 sc1
	global_load_dword v6, v1, s[10:11] offset:2560 sc1
	global_load_dword v7, v1, s[10:11] offset:2816 sc1
	global_load_dword v8, v1, s[10:11] offset:3072 sc1
	global_load_dword v9, v1, s[10:11] offset:3328 sc1
	global_load_dword v10, v1, s[10:11] offset:3584 sc1
	global_load_dword v11, v1, s[10:11] offset:3840 sc1
	global_load_dword v12, v1, s[84:85] sc1
	global_load_dword v13, v1, s[60:61] sc1
	global_load_dword v14, v1, s[4:5] sc1
	global_load_dword v15, v1, s[14:15] sc1
	s_mov_b64 s[12:13], -1
	s_mov_b64 s[16:17], -1
	s_waitcnt vmcnt(14)
	v_add_u32_e32 v17, v0, v16
	s_waitcnt vmcnt(13)
	v_add_u32_e32 v17, v17, v2
	s_waitcnt vmcnt(12)
	v_add_u32_e32 v17, v17, v3
	s_waitcnt vmcnt(11)
	v_add_u32_e32 v17, v17, v4
	s_waitcnt vmcnt(10)
	v_add_u32_e32 v17, v17, v5
	s_waitcnt vmcnt(9)
	v_add_u32_e32 v17, v17, v6
	s_waitcnt vmcnt(8)
	v_add_u32_e32 v17, v17, v7
	s_waitcnt vmcnt(7)
	v_add_u32_e32 v17, v17, v8
	s_waitcnt vmcnt(6)
	v_add_u32_e32 v17, v17, v9
	s_waitcnt vmcnt(5)
	v_add_u32_e32 v17, v17, v10
	s_waitcnt vmcnt(4)
	v_add_u32_e32 v17, v17, v11
	s_waitcnt vmcnt(3)
	v_add_u32_e32 v17, v17, v12
	s_waitcnt vmcnt(2)
	v_add_u32_e32 v17, v17, v13
	s_waitcnt vmcnt(1)
	v_add_u32_e32 v17, v17, v14
	s_waitcnt vmcnt(0)
	v_add_u32_e32 v17, v17, v15
	v_cmp_eq_u32_e32 vcc, s97, v17
	s_cbranch_vccnz .LBB0_390
	s_and_b32 s12, s20, 0xff
	s_cmp_eq_u32 s12, 0
	s_mov_b64 s[12:13], -1
	s_mov_b64 s[18:19], -1
	s_cbranch_scc0 .LBB0_395
	global_load_dword v17, v1, s[90:91] sc1
	s_waitcnt vmcnt(0)
	v_cmp_eq_u32_e32 vcc, 0, v17
	s_cbranch_vccnz .LBB0_397
	s_mov_b64 s[18:19], 0

.LBB0_407:
	s_and_b32 s21, s20, 0xff
	s_mov_b64 s[34:35], -1
	s_cmp_lg_u32 s21, 0
	s_mov_b64 s[38:39], -1
	s_cbranch_scc1 .LBB0_410
	global_load_dword v2, v1, s[90:91] sc1
	s_waitcnt vmcnt(0)
	v_cmp_eq_u32_e32 vcc, 0, v2
	s_cbranch_vccnz .LBB0_412
	s_mov_b64 s[38:39], 0
	s_mov_b64 s[36:37], -1

.LBB0_711:
	s_and_b32 s21, s20, 0xff
	s_mov_b64 s[36:37], -1
	s_cmp_lg_u32 s21, 0
	s_mov_b64 s[40:41], -1
	s_cbranch_scc1 .LBB0_714
	global_load_dword v2, v1, s[90:91] sc1
	s_waitcnt vmcnt(0)
	v_cmp_eq_u32_e32 vcc, 0, v2
	s_cbranch_vccnz .LBB0_716
	s_mov_b64 s[40:41], 0
	s_mov_b64 s[38:39], -1

; __device__ __forceinline__ unsigned xb_ld(unsigned* p)              { return __hip_atomic_load(p, __ATOMIC_RELAXED, __HIP_MEMORY_SCOPE_AGENT); }
; __device__ __forceinline__ void xcd_barrier_complete(unsigned* bar, unsigned x, unsigned& nloc, unsigned& nx) {
;     const unsigned G = gridDim.x * gridDim.y * gridDim.z;
;     unsigned sum, cnt, mine, sp = 0u;
;     for (;;) {
;         sum = 0u; cnt = 0u; mine = 0u;
; #pragma unroll
;         for (unsigned j = 0; j < 16; ++j) { const unsigned c = xb_ld(&bar[XB_XCNT(j)]); sum += c; cnt += (c > 0u) ? 1u : 0u; mine = (j == x) ? c : mine; }
;         if (sum == G) break;
;         __builtin_amdgcn_s_sleep(1);
;         if ((++sp & 255u) == 0u) { if (xb_ld(&bar[XB_TMO])) break; if (sp > XB_SPIN_CAP) { atomicAdd(&bar[XB_TMO], 1u); break; } }
;     }
;     nloc = mine > 0u ? mine : 1u; nx = cnt > 0u ? cnt : 1u;
; }
.LBB0_824:
	global_load_dword v16, v1, s[10:11] offset:1024 sc1
	global_load_dword v0, v1, s[10:11] offset:1280 sc1
	s_waitcnt lgkmcnt(0)
	global_load_dword v2, v1, s[10:11] offset:1536 sc1
	global_load_dword v3, v1, s[10:11] offset:1792 sc1
	global_load_dword v4, v1, s[10:11] offset:2048 sc1
	global_load_dword v5, v1, s[10:11] offset:2304 sc1
	global_load_dword v6, v1, s[10:11] offset:2560 sc1
	global_load_dword v7, v1, s[10:11] offset:2816 sc1
	global_load_dword v8, v1, s[10:11] offset:3072 sc1
	global_load_dword v9, v1, s[10:11] offset:3328 sc1
	global_load_dword v10, v1, s[10:11] offset:3584 sc1
	global_load_dword v11, v1, s[10:11] offset:3840 sc1
	global_load_dword v12, v1, s[84:85] sc1
	global_load_dword v13, v1, s[60:61] sc1
	global_load_dword v14, v1, s[4:5] sc1
	global_load_dword v15, v1, s[14:15] sc1
	s_mov_b64 s[12:13], -1
	s_mov_b64 s[16:17], -1
	s_waitcnt vmcnt(14)
	v_add_u32_e32 v17, v0, v16
	s_waitcnt vmcnt(13)
	v_add_u32_e32 v17, v17, v2
	s_waitcnt vmcnt(12)
	v_add_u32_e32 v17, v17, v3
	s_waitcnt vmcnt(11)
	v_add_u32_e32 v17, v17, v4
	s_waitcnt vmcnt(10)
	v_add_u32_e32 v17, v17, v5
	s_waitcnt vmcnt(9)
	v_add_u32_e32 v17, v17, v6
	s_waitcnt vmcnt(8)
	v_add_u32_e32 v17, v17, v7
	s_waitcnt vmcnt(7)
	v_add_u32_e32 v17, v17, v8
	s_waitcnt vmcnt(6)
	v_add_u32_e32 v17, v17, v9
	s_waitcnt vmcnt(5)
	v_add_u32_e32 v17, v17, v10
	s_waitcnt vmcnt(4)
	v_add_u32_e32 v17, v17, v11
	s_waitcnt vmcnt(3)
	v_add_u32_e32 v17, v17, v12
	s_waitcnt vmcnt(2)
	v_add_u32_e32 v17, v17, v13
	s_waitcnt vmcnt(1)
	v_add_u32_e32 v17, v17, v14
	s_waitcnt vmcnt(0)
	v_add_u32_e32 v17, v17, v15
	v_cmp_eq_u32_e32 vcc, s97, v17
	s_cbranch_vccnz .LBB0_823
	s_and_b32 s12, s22, 0xff
	s_cmp_eq_u32 s12, 0
	s_mov_b64 s[12:13], -1
	s_mov_b64 s[30:31], -1
	s_cbranch_scc0 .LBB0_828
	global_load_dword v17, v1, s[90:91] sc1
	s_waitcnt vmcnt(0)
	v_cmp_eq_u32_e32 vcc, 0, v17
	s_cbranch_vccnz .LBB0_830
	s_mov_b64 s[30:31], 0

.LBB0_840:
	s_and_b32 s38, s22, 0xff
	s_mov_b64 s[36:37], -1
	s_cmp_lg_u32 s38, 0
	s_mov_b64 s[40:41], -1
	s_cbranch_scc1 .LBB0_843
	global_load_dword v2, v1, s[90:91] sc1
	s_waitcnt vmcnt(0)
	v_cmp_eq_u32_e32 vcc, 0, v2
	s_cbranch_vccnz .LBB0_845
	s_mov_b64 s[40:41], 0
	s_mov_b64 s[38:39], -1

.LBB0_907:
	s_and_b32 s34, s22, 0xff
	s_mov_b64 s[30:31], -1
	s_cmp_lg_u32 s34, 0
	s_mov_b64 s[36:37], -1
	s_cbranch_scc1 .LBB0_910
	global_load_dword v2, v1, s[90:91] sc1
	s_waitcnt vmcnt(0)
	v_cmp_eq_u32_e32 vcc, 0, v2
	s_cbranch_vccnz .LBB0_912
	s_mov_b64 s[36:37], 0
	s_mov_b64 s[34:35], -1
